# code placement: K-loop heads aligned to 128 bytes instead of 64
# baseline (speedup 1.0000x reference)
; DI void gemm_stream2(const bf16_t* __restrict__ A, int lda, const bf16_t* __restrict__ Bt, int ldb, int K, int m0, int n0, ...
;     ...
;     for (int kt = 0; kt < nk; ++kt) {
;         const bool pf = (kt + 2 < nk) || has_next, more = (kt + 1 < nk) || has_next;
; DI void zero_acc(f32x4 (&acc)[4][4]) {
; #pragma unroll
;     for (int i = 0; i < 4; ++i)
; #pragma unroll
;         for (int j = 0; j < 4; ++j) acc[i][j] = (f32x4){0.f, 0.f, 0.f, 0.f};
; }
.Lgu_nonext:
	v_mov_b64_e32 v[24:25], 0
	v_mov_b64_e32 v[26:27], 0
	v_mov_b64_e32 v[28:29], 0
	v_mov_b64_e32 v[30:31], 0
	v_mov_b64_e32 v[32:33], 0
	v_mov_b64_e32 v[34:35], 0
	v_mov_b64_e32 v[36:37], 0
	v_mov_b64_e32 v[38:39], 0
	v_mov_b64_e32 v[40:41], 0
	v_mov_b64_e32 v[42:43], 0
	v_mov_b64_e32 v[44:45], 0
	v_mov_b64_e32 v[46:47], 0
	v_mov_b64_e32 v[48:49], 0
	v_mov_b64_e32 v[50:51], 0
	v_mov_b64_e32 v[52:53], 0
	v_mov_b64_e32 v[54:55], 0
	v_mov_b64_e32 v[56:57], 0
	v_mov_b64_e32 v[58:59], 0
	v_mov_b64_e32 v[60:61], 0
	v_mov_b64_e32 v[62:63], 0
	v_mov_b64_e32 v[64:65], 0
	v_mov_b64_e32 v[66:67], 0
	v_mov_b64_e32 v[68:69], 0
	v_mov_b64_e32 v[70:71], 0
	v_mov_b64_e32 v[72:73], 0
	v_mov_b64_e32 v[74:75], 0
	v_mov_b64_e32 v[76:77], 0
	v_mov_b64_e32 v[78:79], 0
	v_mov_b64_e32 v[80:81], 0
	v_mov_b64_e32 v[82:83], 0
	v_mov_b64_e32 v[84:85], 0
	v_mov_b64_e32 v[86:87], 0
	v_mov_b64_e32 v[88:89], 0
	v_mov_b64_e32 v[90:91], 0
	v_mov_b64_e32 v[92:93], 0
	v_mov_b64_e32 v[94:95], 0
	v_mov_b64_e32 v[96:97], 0
	v_mov_b64_e32 v[98:99], 0
	v_mov_b64_e32 v[100:101], 0
	v_mov_b64_e32 v[102:103], 0
	v_mov_b64_e32 v[104:105], 0
	v_mov_b64_e32 v[106:107], 0
	v_mov_b64_e32 v[108:109], 0
	v_mov_b64_e32 v[110:111], 0
	v_mov_b64_e32 v[112:113], 0
	v_mov_b64_e32 v[114:115], 0
	v_mov_b64_e32 v[116:117], 0
	v_mov_b64_e32 v[118:119], 0
	v_mov_b64_e32 v[120:121], 0
	v_mov_b64_e32 v[122:123], 0
	v_mov_b64_e32 v[124:125], 0
	v_mov_b64_e32 v[126:127], 0
	v_mov_b64_e32 v[128:129], 0
	v_mov_b64_e32 v[130:131], 0
	v_mov_b64_e32 v[132:133], 0
	v_mov_b64_e32 v[134:135], 0
	v_mov_b64_e32 v[136:137], 0
	v_mov_b64_e32 v[138:139], 0
	v_mov_b64_e32 v[140:141], 0
	v_mov_b64_e32 v[142:143], 0
	v_mov_b64_e32 v[144:145], 0
	v_mov_b64_e32 v[146:147], 0
	v_mov_b64_e32 v[148:149], 0
	v_mov_b64_e32 v[150:151], 0
	s_add_u32 s0, s54, 7
	.p2alignl 7, 3212836864

; DI void gemm_stream2(const bf16_t* __restrict__ A, int lda, const bf16_t* __restrict__ Bt, int ldb, int K, int m0, int n0, ...
;     ...
;     for (int kt = 0; kt < nk; ++kt) {
;         const bool pf = (kt + 2 < nk) || has_next, more = (kt + 1 < nk) || has_next;
; DI void zero_acc(f32x4 (&acc)[4][4]) {
; #pragma unroll
;     for (int i = 0; i < 4; ++i)
; #pragma unroll
;         for (int j = 0; j < 4; ++j) acc[i][j] = (f32x4){0.f, 0.f, 0.f, 0.f};
; }
.Lgyd_nx_done:
	v_mov_b64_e32 v[24:25], 0
	v_mov_b64_e32 v[26:27], 0
	v_mov_b64_e32 v[28:29], 0
	v_mov_b64_e32 v[30:31], 0
	v_mov_b64_e32 v[32:33], 0
	v_mov_b64_e32 v[34:35], 0
	v_mov_b64_e32 v[36:37], 0
	v_mov_b64_e32 v[38:39], 0
	v_mov_b64_e32 v[40:41], 0
	v_mov_b64_e32 v[42:43], 0
	v_mov_b64_e32 v[44:45], 0
	v_mov_b64_e32 v[46:47], 0
	v_mov_b64_e32 v[48:49], 0
	v_mov_b64_e32 v[50:51], 0
	v_mov_b64_e32 v[52:53], 0
	v_mov_b64_e32 v[54:55], 0
	v_mov_b64_e32 v[56:57], 0
	v_mov_b64_e32 v[58:59], 0
	v_mov_b64_e32 v[60:61], 0
	v_mov_b64_e32 v[62:63], 0
	v_mov_b64_e32 v[64:65], 0
	v_mov_b64_e32 v[66:67], 0
	v_mov_b64_e32 v[68:69], 0
	v_mov_b64_e32 v[70:71], 0
	v_mov_b64_e32 v[72:73], 0
	v_mov_b64_e32 v[74:75], 0
	v_mov_b64_e32 v[76:77], 0
	v_mov_b64_e32 v[78:79], 0
	v_mov_b64_e32 v[80:81], 0
	v_mov_b64_e32 v[82:83], 0
	v_mov_b64_e32 v[84:85], 0
	v_mov_b64_e32 v[86:87], 0
	v_mov_b64_e32 v[88:89], 0
	v_mov_b64_e32 v[90:91], 0
	v_mov_b64_e32 v[92:93], 0
	v_mov_b64_e32 v[94:95], 0
	v_mov_b64_e32 v[96:97], 0
	v_mov_b64_e32 v[98:99], 0
	v_mov_b64_e32 v[100:101], 0
	v_mov_b64_e32 v[102:103], 0
	v_mov_b64_e32 v[104:105], 0
	v_mov_b64_e32 v[106:107], 0
	v_mov_b64_e32 v[108:109], 0
	v_mov_b64_e32 v[110:111], 0
	v_mov_b64_e32 v[112:113], 0
	v_mov_b64_e32 v[114:115], 0
	v_mov_b64_e32 v[116:117], 0
	v_mov_b64_e32 v[118:119], 0
	v_mov_b64_e32 v[120:121], 0
	v_mov_b64_e32 v[122:123], 0
	v_mov_b64_e32 v[124:125], 0
	v_mov_b64_e32 v[126:127], 0
	v_mov_b64_e32 v[128:129], 0
	v_mov_b64_e32 v[130:131], 0
	v_mov_b64_e32 v[132:133], 0
	v_mov_b64_e32 v[134:135], 0
	v_mov_b64_e32 v[136:137], 0
	v_mov_b64_e32 v[138:139], 0
	v_mov_b64_e32 v[140:141], 0
	v_mov_b64_e32 v[142:143], 0
	v_mov_b64_e32 v[144:145], 0
	v_mov_b64_e32 v[146:147], 0
	v_mov_b64_e32 v[148:149], 0
	v_mov_b64_e32 v[150:151], 0
	s_cmp_eq_u32 s55, 0
	s_cselect_b32 s0, 21, 1
	s_add_u32 s0, s0, s54
	s_cmp_eq_u32 s0, 0
	s_cbranch_scc1 .Lgyd_kdone
	.p2alignl 7, 3212836864

; DI void gemm_stream2(const bf16_t* __restrict__ A, int lda, const bf16_t* __restrict__ Bt, int ldb, int K, int m0, int n0, ...
;     ...
;     for (int kt = 0; kt < nk; ++kt) {
;         const bool pf = (kt + 2 < nk) || has_next, more = (kt + 1 < nk) || has_next;
; DI void zero_acc(f32x4 (&acc)[4][4]) {
; #pragma unroll
;     for (int i = 0; i < 4; ++i)
; #pragma unroll
;         for (int j = 0; j < 4; ++j) acc[i][j] = (f32x4){0.f, 0.f, 0.f, 0.f};
; }
.Lgyo_nx_done:
	v_mov_b64_e32 v[24:25], 0
	v_mov_b64_e32 v[26:27], 0
	v_mov_b64_e32 v[28:29], 0
	v_mov_b64_e32 v[30:31], 0
	v_mov_b64_e32 v[32:33], 0
	v_mov_b64_e32 v[34:35], 0
	v_mov_b64_e32 v[36:37], 0
	v_mov_b64_e32 v[38:39], 0
	v_mov_b64_e32 v[40:41], 0
	v_mov_b64_e32 v[42:43], 0
	v_mov_b64_e32 v[44:45], 0
	v_mov_b64_e32 v[46:47], 0
	v_mov_b64_e32 v[48:49], 0
	v_mov_b64_e32 v[50:51], 0
	v_mov_b64_e32 v[52:53], 0
	v_mov_b64_e32 v[54:55], 0
	v_mov_b64_e32 v[56:57], 0
	v_mov_b64_e32 v[58:59], 0
	v_mov_b64_e32 v[60:61], 0
	v_mov_b64_e32 v[62:63], 0
	v_mov_b64_e32 v[64:65], 0
	v_mov_b64_e32 v[66:67], 0
	v_mov_b64_e32 v[68:69], 0
	v_mov_b64_e32 v[70:71], 0
	v_mov_b64_e32 v[72:73], 0
	v_mov_b64_e32 v[74:75], 0
	v_mov_b64_e32 v[76:77], 0
	v_mov_b64_e32 v[78:79], 0
	v_mov_b64_e32 v[80:81], 0
	v_mov_b64_e32 v[82:83], 0
	v_mov_b64_e32 v[84:85], 0
	v_mov_b64_e32 v[86:87], 0
	v_mov_b64_e32 v[88:89], 0
	v_mov_b64_e32 v[90:91], 0
	v_mov_b64_e32 v[92:93], 0
	v_mov_b64_e32 v[94:95], 0
	v_mov_b64_e32 v[96:97], 0
	v_mov_b64_e32 v[98:99], 0
	v_mov_b64_e32 v[100:101], 0
	v_mov_b64_e32 v[102:103], 0
	v_mov_b64_e32 v[104:105], 0
	v_mov_b64_e32 v[106:107], 0
	v_mov_b64_e32 v[108:109], 0
	v_mov_b64_e32 v[110:111], 0
	v_mov_b64_e32 v[112:113], 0
	v_mov_b64_e32 v[114:115], 0
	v_mov_b64_e32 v[116:117], 0
	v_mov_b64_e32 v[118:119], 0
	v_mov_b64_e32 v[120:121], 0
	v_mov_b64_e32 v[122:123], 0
	v_mov_b64_e32 v[124:125], 0
	v_mov_b64_e32 v[126:127], 0
	v_mov_b64_e32 v[128:129], 0
	v_mov_b64_e32 v[130:131], 0
	v_mov_b64_e32 v[132:133], 0
	v_mov_b64_e32 v[134:135], 0
	v_mov_b64_e32 v[136:137], 0
	v_mov_b64_e32 v[138:139], 0
	v_mov_b64_e32 v[140:141], 0
	v_mov_b64_e32 v[142:143], 0
	v_mov_b64_e32 v[144:145], 0
	v_mov_b64_e32 v[146:147], 0
	v_mov_b64_e32 v[148:149], 0
	v_mov_b64_e32 v[150:151], 0
	s_cmp_eq_u32 s55, 0
	s_cselect_b32 s0, 7, 0
	s_add_u32 s0, s0, s54
	s_cmp_eq_u32 s0, 0
	s_cbranch_scc1 .Lgyo_kdone
	.p2alignl 7, 3212836864
